# in-proj GEMM: accumulators re-zeroed inside the epilogue after conversion/stores; the 128-instruction zero block runs for the first tile only
# speedup vs baseline: 1.0012x; 1.0012x over previous
.LBB0_139:
	s_ashr_i32 s27, s26, 31
	s_lshl_b64 s[0:1], s[26:27], 20
	s_add_u32 s86, s16, s0
	s_addc_u32 s87, s17, s1
	s_and_b64 s[0:1], s[6:7], exec
	s_cselect_b32 s0, s87, s11
	s_cselect_b32 s1, s86, s10
	s_ashr_i32 s25, s24, 31
	s_lshl_b64 s[14:15], s[24:25], 20
	s_add_u32 s90, s19, s14
	s_addc_u32 s91, s28, s15
	s_and_b64 s[14:15], s[6:7], exec
	s_cselect_b32 s25, s91, s9
	s_cselect_b32 s27, s90, s8
	s_add_u32 s57, s8, 0x100
	s_addc_u32 s58, s9, 0
	s_add_u32 s8, s10, 0x80080
	v_mov_b32_e32 v2, 0
	s_addc_u32 s9, s11, 0
	s_mov_b32 s59, -2
	s_cmp_lg_u32 s54, 1
	s_cbranch_scc1 .Lin_zskip
	v_mov_b32_e32 v3, v2
	v_mov_b32_e32 v4, v2
	v_mov_b32_e32 v5, v2
	v_mov_b32_e32 v6, v2
	v_mov_b32_e32 v7, v2
	v_mov_b32_e32 v8, v2
	v_mov_b32_e32 v9, v2
	v_mov_b32_e32 v18, v2
	v_mov_b32_e32 v19, v2
	v_mov_b32_e32 v20, v2
	v_mov_b32_e32 v21, v2
	v_mov_b32_e32 v22, v2
	v_mov_b32_e32 v23, v2
	v_mov_b32_e32 v24, v2
	v_mov_b32_e32 v25, v2
	v_mov_b32_e32 v34, v2
	v_mov_b32_e32 v35, v2
	v_mov_b32_e32 v36, v2
	v_mov_b32_e32 v37, v2
	v_mov_b32_e32 v38, v2
	v_mov_b32_e32 v39, v2
	v_mov_b32_e32 v40, v2
	v_mov_b32_e32 v41, v2
	v_mov_b32_e32 v50, v2
	v_mov_b32_e32 v51, v2
	v_mov_b32_e32 v52, v2
	v_mov_b32_e32 v53, v2
	v_mov_b32_e32 v54, v2
	v_mov_b32_e32 v55, v2
	v_mov_b32_e32 v56, v2
	v_mov_b32_e32 v57, v2
	v_mov_b32_e32 v10, v2
	v_mov_b32_e32 v11, v2
	v_mov_b32_e32 v12, v2
	v_mov_b32_e32 v13, v2
	v_mov_b32_e32 v14, v2
	v_mov_b32_e32 v15, v2
	v_mov_b32_e32 v16, v2
	v_mov_b32_e32 v17, v2
	v_mov_b32_e32 v26, v2
	v_mov_b32_e32 v27, v2
	v_mov_b32_e32 v28, v2
	v_mov_b32_e32 v29, v2
	v_mov_b32_e32 v30, v2
	v_mov_b32_e32 v31, v2
	v_mov_b32_e32 v32, v2
	v_mov_b32_e32 v33, v2
	v_mov_b32_e32 v42, v2
	v_mov_b32_e32 v43, v2
	v_mov_b32_e32 v44, v2
	v_mov_b32_e32 v45, v2
	v_mov_b32_e32 v46, v2
	v_mov_b32_e32 v47, v2
	v_mov_b32_e32 v48, v2
	v_mov_b32_e32 v49, v2
	v_mov_b32_e32 v58, v2
	v_mov_b32_e32 v59, v2
	v_mov_b32_e32 v60, v2
	v_mov_b32_e32 v61, v2
	v_mov_b32_e32 v62, v2
	v_mov_b32_e32 v63, v2
	v_mov_b32_e32 v64, v2
	v_mov_b32_e32 v65, v2
	v_mov_b32_e32 v66, v2
	v_mov_b32_e32 v67, v2
	v_mov_b32_e32 v68, v2
	v_mov_b32_e32 v69, v2
	v_mov_b32_e32 v70, v2
	v_mov_b32_e32 v71, v2
	v_mov_b32_e32 v72, v2
	v_mov_b32_e32 v73, v2
	v_mov_b32_e32 v82, v2
	v_mov_b32_e32 v83, v2
	v_mov_b32_e32 v84, v2
	v_mov_b32_e32 v85, v2
	v_mov_b32_e32 v86, v2
	v_mov_b32_e32 v87, v2
	v_mov_b32_e32 v88, v2
	v_mov_b32_e32 v89, v2
	v_mov_b32_e32 v98, v2
	v_mov_b32_e32 v99, v2
	v_mov_b32_e32 v100, v2
	v_mov_b32_e32 v101, v2
	v_mov_b32_e32 v102, v2
	v_mov_b32_e32 v103, v2
	v_mov_b32_e32 v104, v2
	v_mov_b32_e32 v105, v2
	v_mov_b32_e32 v114, v2
	v_mov_b32_e32 v115, v2
	v_mov_b32_e32 v116, v2
	v_mov_b32_e32 v117, v2
	v_mov_b32_e32 v118, v2
	v_mov_b32_e32 v119, v2
	v_mov_b32_e32 v120, v2
	v_mov_b32_e32 v121, v2
	v_mov_b32_e32 v74, v2
	v_mov_b32_e32 v75, v2
	v_mov_b32_e32 v76, v2
	v_mov_b32_e32 v77, v2
	v_mov_b32_e32 v78, v2
	v_mov_b32_e32 v79, v2
	v_mov_b32_e32 v80, v2
	v_mov_b32_e32 v81, v2
	v_mov_b32_e32 v90, v2
	v_mov_b32_e32 v91, v2
	v_mov_b32_e32 v92, v2
	v_mov_b32_e32 v93, v2
	v_mov_b32_e32 v94, v2
	v_mov_b32_e32 v95, v2
	v_mov_b32_e32 v96, v2
	v_mov_b32_e32 v97, v2
	v_mov_b32_e32 v106, v2
	v_mov_b32_e32 v107, v2
	v_mov_b32_e32 v108, v2
	v_mov_b32_e32 v109, v2
	v_mov_b32_e32 v110, v2
	v_mov_b32_e32 v111, v2
	v_mov_b32_e32 v112, v2
	v_mov_b32_e32 v113, v2
	v_mov_b32_e32 v122, v2
	v_mov_b32_e32 v123, v2
	v_mov_b32_e32 v124, v2
	v_mov_b32_e32 v125, v2
	v_mov_b32_e32 v126, v2
	v_mov_b32_e32 v127, v2
	v_mov_b32_e32 v128, v2
	v_mov_b32_e32 v129, v2
.Lin_zskip:
.LBB0_140:
	s_add_u32 s10, s8, 0xfff80080
	s_addc_u32 s11, s9, -1
	s_add_i32 s60, 0, 0x10000
	s_cmp_eq_u32 s59, 28
	s_cselect_b32 s15, s0, s11
	s_cselect_b32 s14, s1, s10
	v_add_u32_e32 v0, s60, v167
	s_cselect_b32 s11, s25, s58
	s_cselect_b32 s10, s27, s57
	s_add_i32 s62, 0, 0x14000
	ds_read_b128 v[130:133], v0
	ds_read_b128 v[158:161], v0 offset:1024
	ds_read_b128 v[162:165], v0 offset:2048
	ds_read_b128 v[170:173], v0 offset:3072
	v_add_u32_e32 v0, s62, v167
	ds_read_b128 v[174:177], v0
	ds_read_b128 v[178:181], v0 offset:1024
	ds_read_b128 v[182:185], v0 offset:2048
	ds_read_b128 v[186:189], v0 offset:3072
	s_mov_b32 m0, s52
	s_nop 0
	global_load_lds_dwordx4 v140, s[74:75]
	s_mov_b32 m0, s53
	s_nop 0
	global_load_lds_dwordx4 v136, s[74:75]
	s_add_i32 m0, s48, 0xc000
	ds_read_b128 v[190:193], v169
	ds_read_b128 v[194:197], v169 offset:1024
	ds_read_b128 v[198:201], v169 offset:2048
	ds_read_b128 v[216:219], v169 offset:3072
	ds_read_b128 v[220:223], v169 offset:4096
	ds_read_b128 v[224:227], v169 offset:5120
	ds_read_b128 v[228:231], v169 offset:6144
	ds_read_b128 v[232:235], v169 offset:7168
	global_load_lds_dwordx4 v156, s[8:9]
	s_add_i32 m0, s48, 0xe000
	s_nop 0
	global_load_lds_dwordx4 v146, s[8:9]
	s_waitcnt vmcnt(8)
	s_waitcnt lgkmcnt(0)
	s_barrier
	s_setprio 1
	s_waitcnt lgkmcnt(0)
	v_mfma_f32_16x16x32_bf16 v[126:129], v[130:133], v[190:193], v[126:129]
	v_mfma_f32_16x16x32_bf16 v[122:125], v[162:165], v[190:193], v[122:125]
	v_mfma_f32_16x16x32_bf16 v[110:113], v[130:133], v[198:201], v[110:113]
	v_mfma_f32_16x16x32_bf16 v[106:109], v[162:165], v[198:201], v[106:109]
	v_mfma_f32_16x16x32_bf16 v[94:97], v[130:133], v[220:223], v[94:97]
	v_mfma_f32_16x16x32_bf16 v[90:93], v[162:165], v[220:223], v[90:93]
	v_mfma_f32_16x16x32_bf16 v[78:81], v[130:133], v[228:231], v[78:81]
	v_mfma_f32_16x16x32_bf16 v[74:77], v[162:165], v[228:231], v[74:77]
	v_mfma_f32_16x16x32_bf16 v[126:129], v[158:161], v[194:197], v[126:129]
	v_mfma_f32_16x16x32_bf16 v[122:125], v[170:173], v[194:197], v[122:125]
	v_mfma_f32_16x16x32_bf16 v[110:113], v[158:161], v[216:219], v[110:113]
	v_mfma_f32_16x16x32_bf16 v[106:109], v[170:173], v[216:219], v[106:109]
	v_mfma_f32_16x16x32_bf16 v[94:97], v[158:161], v[224:227], v[94:97]
	v_mfma_f32_16x16x32_bf16 v[90:93], v[170:173], v[224:227], v[90:93]
	v_mfma_f32_16x16x32_bf16 v[78:81], v[158:161], v[232:235], v[78:81]
	v_mfma_f32_16x16x32_bf16 v[74:77], v[170:173], v[232:235], v[74:77]
	s_setprio 0
	s_setprio 1
	v_mfma_f32_16x16x32_bf16 v[118:121], v[174:177], v[190:193], v[118:121]
	v_mfma_f32_16x16x32_bf16 v[114:117], v[182:185], v[190:193], v[114:117]
	v_mfma_f32_16x16x32_bf16 v[102:105], v[174:177], v[198:201], v[102:105]
	v_mfma_f32_16x16x32_bf16 v[98:101], v[182:185], v[198:201], v[98:101]
	v_mfma_f32_16x16x32_bf16 v[86:89], v[174:177], v[220:223], v[86:89]
	v_mfma_f32_16x16x32_bf16 v[82:85], v[182:185], v[220:223], v[82:85]
	v_mfma_f32_16x16x32_bf16 v[70:73], v[174:177], v[228:231], v[70:73]
	v_mfma_f32_16x16x32_bf16 v[66:69], v[182:185], v[228:231], v[66:69]
	v_mfma_f32_16x16x32_bf16 v[118:121], v[178:181], v[194:197], v[118:121]
	v_mfma_f32_16x16x32_bf16 v[114:117], v[186:189], v[194:197], v[114:117]
	v_mfma_f32_16x16x32_bf16 v[102:105], v[178:181], v[216:219], v[102:105]
	v_mfma_f32_16x16x32_bf16 v[98:101], v[186:189], v[216:219], v[98:101]
	v_mfma_f32_16x16x32_bf16 v[86:89], v[178:181], v[224:227], v[86:89]
	v_mfma_f32_16x16x32_bf16 v[82:85], v[186:189], v[224:227], v[82:85]
	v_mfma_f32_16x16x32_bf16 v[70:73], v[178:181], v[232:235], v[70:73]
	v_mfma_f32_16x16x32_bf16 v[66:69], v[186:189], v[232:235], v[66:69]
	s_setprio 0
	s_barrier
	s_add_i32 s60, s60, s29
	s_add_u32 s72, s10, s44
	s_addc_u32 s73, s11, s45
	s_mov_b32 m0, s60
	ds_read_b128 v[190:193], v169 offset:16384
	ds_read_b128 v[194:197], v169 offset:17408
	ds_read_b128 v[198:201], v169 offset:18432
	ds_read_b128 v[216:219], v169 offset:19456
	ds_read_b128 v[220:223], v169 offset:20480
	ds_read_b128 v[224:227], v169 offset:21504
	ds_read_b128 v[228:231], v169 offset:22528
	ds_read_b128 v[232:235], v169 offset:23552
	global_load_lds_dwordx4 v138, s[10:11]
	s_add_i32 m0, s60, 0x2000
	s_add_u32 s60, s10, 0x80000
	s_addc_u32 s61, s11, 0
	s_add_i32 s62, s62, s29
	global_load_lds_dwordx4 v134, s[10:11]
	s_mov_b32 m0, s62
	s_add_u32 s74, s14, s44
	s_addc_u32 s75, s15, s45
	global_load_lds_dwordx4 v138, s[60:61]
	s_add_i32 m0, s62, 0x2000
	s_nop 0
	global_load_lds_dwordx4 v134, s[60:61]
	s_waitcnt vmcnt(6)
	s_waitcnt lgkmcnt(0)
	s_barrier
	s_setprio 1
	s_waitcnt lgkmcnt(0)
	v_mfma_f32_16x16x32_bf16 v[62:65], v[130:133], v[190:193], v[62:65]
	v_mfma_f32_16x16x32_bf16 v[58:61], v[162:165], v[190:193], v[58:61]
	v_mfma_f32_16x16x32_bf16 v[46:49], v[130:133], v[198:201], v[46:49]
	v_mfma_f32_16x16x32_bf16 v[42:45], v[162:165], v[198:201], v[42:45]
	v_mfma_f32_16x16x32_bf16 v[30:33], v[130:133], v[220:223], v[30:33]
	v_mfma_f32_16x16x32_bf16 v[26:29], v[162:165], v[220:223], v[26:29]
	v_mfma_f32_16x16x32_bf16 v[14:17], v[130:133], v[228:231], v[14:17]
	v_mfma_f32_16x16x32_bf16 v[10:13], v[162:165], v[228:231], v[10:13]
	v_mfma_f32_16x16x32_bf16 v[62:65], v[158:161], v[194:197], v[62:65]
	v_mfma_f32_16x16x32_bf16 v[58:61], v[170:173], v[194:197], v[58:61]
	v_mfma_f32_16x16x32_bf16 v[46:49], v[158:161], v[216:219], v[46:49]
	v_mfma_f32_16x16x32_bf16 v[42:45], v[170:173], v[216:219], v[42:45]
	v_mfma_f32_16x16x32_bf16 v[30:33], v[158:161], v[224:227], v[30:33]
	v_mfma_f32_16x16x32_bf16 v[26:29], v[170:173], v[224:227], v[26:29]
	v_mfma_f32_16x16x32_bf16 v[14:17], v[158:161], v[232:235], v[14:17]
	v_mfma_f32_16x16x32_bf16 v[10:13], v[170:173], v[232:235], v[10:13]
	s_setprio 0
	s_setprio 1
	v_mfma_f32_16x16x32_bf16 v[54:57], v[174:177], v[190:193], v[54:57]
	v_mfma_f32_16x16x32_bf16 v[50:53], v[182:185], v[190:193], v[50:53]
	v_mfma_f32_16x16x32_bf16 v[38:41], v[174:177], v[198:201], v[38:41]
	v_mfma_f32_16x16x32_bf16 v[34:37], v[182:185], v[198:201], v[34:37]
	v_mfma_f32_16x16x32_bf16 v[22:25], v[174:177], v[220:223], v[22:25]
	v_mfma_f32_16x16x32_bf16 v[18:21], v[182:185], v[220:223], v[18:21]
	v_mfma_f32_16x16x32_bf16 v[6:9], v[174:177], v[228:231], v[6:9]
	v_mfma_f32_16x16x32_bf16 v[2:5], v[182:185], v[228:231], v[2:5]
	v_mfma_f32_16x16x32_bf16 v[54:57], v[178:181], v[194:197], v[54:57]
	v_mfma_f32_16x16x32_bf16 v[50:53], v[186:189], v[194:197], v[50:53]
	v_mfma_f32_16x16x32_bf16 v[38:41], v[178:181], v[216:219], v[38:41]
	v_mfma_f32_16x16x32_bf16 v[34:37], v[186:189], v[216:219], v[34:37]
	v_mfma_f32_16x16x32_bf16 v[22:25], v[178:181], v[224:227], v[22:25]
	v_mfma_f32_16x16x32_bf16 v[18:21], v[186:189], v[224:227], v[18:21]
	v_mfma_f32_16x16x32_bf16 v[6:9], v[178:181], v[232:235], v[6:9]
	v_mfma_f32_16x16x32_bf16 v[2:5], v[186:189], v[232:235], v[2:5]
	s_setprio 0
	s_barrier
	s_add_i32 s60, 0, 0x18000
	v_add_u32_e32 v0, s60, v167
	s_add_i32 s61, 0, 0x1c000
	ds_read_b128 v[130:133], v0
	ds_read_b128 v[158:161], v0 offset:1024
	ds_read_b128 v[162:165], v0 offset:2048
	ds_read_b128 v[170:173], v0 offset:3072
	v_add_u32_e32 v0, s61, v167
	ds_read_b128 v[174:177], v0
	ds_read_b128 v[178:181], v0 offset:1024
	ds_read_b128 v[182:185], v0 offset:2048
	ds_read_b128 v[186:189], v0 offset:3072
	s_mov_b32 m0, s48
	s_nop 0
	global_load_lds_dwordx4 v140, s[14:15]
	s_mov_b32 m0, s49
	s_nop 0
	global_load_lds_dwordx4 v136, s[14:15]
	s_add_u32 s14, s14, 0x80000
	s_addc_u32 s15, s15, 0
	s_mov_b32 m0, s50
	ds_read_b128 v[190:193], v169 offset:32768
	ds_read_b128 v[194:197], v169 offset:33792
	ds_read_b128 v[198:201], v169 offset:34816
	ds_read_b128 v[216:219], v169 offset:35840
	ds_read_b128 v[220:223], v169 offset:36864
	ds_read_b128 v[224:227], v169 offset:37888
	ds_read_b128 v[228:231], v169 offset:38912
	ds_read_b128 v[232:235], v169 offset:39936
	global_load_lds_dwordx4 v140, s[14:15]
	s_mov_b32 m0, s51
	s_nop 0
	global_load_lds_dwordx4 v136, s[14:15]
	s_waitcnt vmcnt(8)
	s_waitcnt lgkmcnt(0)
	s_barrier
	s_setprio 1
	s_waitcnt lgkmcnt(0)
	v_mfma_f32_16x16x32_bf16 v[126:129], v[130:133], v[190:193], v[126:129]
	v_mfma_f32_16x16x32_bf16 v[122:125], v[162:165], v[190:193], v[122:125]
	v_mfma_f32_16x16x32_bf16 v[110:113], v[130:133], v[198:201], v[110:113]
	v_mfma_f32_16x16x32_bf16 v[106:109], v[162:165], v[198:201], v[106:109]
	v_mfma_f32_16x16x32_bf16 v[94:97], v[130:133], v[220:223], v[94:97]
	v_mfma_f32_16x16x32_bf16 v[90:93], v[162:165], v[220:223], v[90:93]
	v_mfma_f32_16x16x32_bf16 v[78:81], v[130:133], v[228:231], v[78:81]
	v_mfma_f32_16x16x32_bf16 v[74:77], v[162:165], v[228:231], v[74:77]
	v_mfma_f32_16x16x32_bf16 v[126:129], v[158:161], v[194:197], v[126:129]
	v_mfma_f32_16x16x32_bf16 v[122:125], v[170:173], v[194:197], v[122:125]
	v_mfma_f32_16x16x32_bf16 v[110:113], v[158:161], v[216:219], v[110:113]
	v_mfma_f32_16x16x32_bf16 v[106:109], v[170:173], v[216:219], v[106:109]
	v_mfma_f32_16x16x32_bf16 v[94:97], v[158:161], v[224:227], v[94:97]
	v_mfma_f32_16x16x32_bf16 v[90:93], v[170:173], v[224:227], v[90:93]
	v_mfma_f32_16x16x32_bf16 v[78:81], v[158:161], v[232:235], v[78:81]
	v_mfma_f32_16x16x32_bf16 v[74:77], v[170:173], v[232:235], v[74:77]
	s_setprio 0
	s_setprio 1
	v_mfma_f32_16x16x32_bf16 v[118:121], v[174:177], v[190:193], v[118:121]
	v_mfma_f32_16x16x32_bf16 v[114:117], v[182:185], v[190:193], v[114:117]
	v_mfma_f32_16x16x32_bf16 v[102:105], v[174:177], v[198:201], v[102:105]
	v_mfma_f32_16x16x32_bf16 v[98:101], v[182:185], v[198:201], v[98:101]
	v_mfma_f32_16x16x32_bf16 v[86:89], v[174:177], v[220:223], v[86:89]
	v_mfma_f32_16x16x32_bf16 v[82:85], v[182:185], v[220:223], v[82:85]
	v_mfma_f32_16x16x32_bf16 v[70:73], v[174:177], v[228:231], v[70:73]
	v_mfma_f32_16x16x32_bf16 v[66:69], v[182:185], v[228:231], v[66:69]
	v_mfma_f32_16x16x32_bf16 v[118:121], v[178:181], v[194:197], v[118:121]
	v_mfma_f32_16x16x32_bf16 v[114:117], v[186:189], v[194:197], v[114:117]
	v_mfma_f32_16x16x32_bf16 v[102:105], v[178:181], v[216:219], v[102:105]
	v_mfma_f32_16x16x32_bf16 v[98:101], v[186:189], v[216:219], v[98:101]
	v_mfma_f32_16x16x32_bf16 v[86:89], v[178:181], v[224:227], v[86:89]
	v_mfma_f32_16x16x32_bf16 v[82:85], v[186:189], v[224:227], v[82:85]
	v_mfma_f32_16x16x32_bf16 v[70:73], v[178:181], v[232:235], v[70:73]
	v_mfma_f32_16x16x32_bf16 v[66:69], v[186:189], v[232:235], v[66:69]
	s_setprio 0
	s_barrier
	s_add_i32 s14, s60, s29
	s_mov_b32 m0, s14
	ds_read_b128 v[190:193], v169 offset:49152
	ds_read_b128 v[194:197], v169 offset:50176
	ds_read_b128 v[198:201], v169 offset:51200
	ds_read_b128 v[216:219], v169 offset:52224
	ds_read_b128 v[220:223], v169 offset:53248
	ds_read_b128 v[224:227], v169 offset:54272
	ds_read_b128 v[228:231], v169 offset:55296
	ds_read_b128 v[232:235], v169 offset:56320
	global_load_lds_dwordx4 v138, s[72:73]
	s_add_i32 m0, s14, 0x2000
	s_add_u32 s10, s10, 0x80080
	s_addc_u32 s11, s11, 0
	s_add_i32 s14, s61, s29
	global_load_lds_dwordx4 v134, s[72:73]
	s_mov_b32 m0, s14
	s_nop 0
	global_load_lds_dwordx4 v138, s[10:11]
	s_add_i32 m0, s14, 0x2000
	s_nop 0
	global_load_lds_dwordx4 v134, s[10:11]
	s_waitcnt vmcnt(6)
	s_waitcnt lgkmcnt(0)
	s_barrier
	s_setprio 1
	s_waitcnt lgkmcnt(0)
	v_mfma_f32_16x16x32_bf16 v[62:65], v[130:133], v[190:193], v[62:65]
	v_mfma_f32_16x16x32_bf16 v[58:61], v[162:165], v[190:193], v[58:61]
	v_mfma_f32_16x16x32_bf16 v[46:49], v[130:133], v[198:201], v[46:49]
	v_mfma_f32_16x16x32_bf16 v[42:45], v[162:165], v[198:201], v[42:45]
	v_mfma_f32_16x16x32_bf16 v[30:33], v[130:133], v[220:223], v[30:33]
	v_mfma_f32_16x16x32_bf16 v[26:29], v[162:165], v[220:223], v[26:29]
	v_mfma_f32_16x16x32_bf16 v[14:17], v[130:133], v[228:231], v[14:17]
	v_mfma_f32_16x16x32_bf16 v[10:13], v[162:165], v[228:231], v[10:13]
	v_mfma_f32_16x16x32_bf16 v[62:65], v[158:161], v[194:197], v[62:65]
	v_mfma_f32_16x16x32_bf16 v[58:61], v[170:173], v[194:197], v[58:61]
	v_mfma_f32_16x16x32_bf16 v[46:49], v[158:161], v[216:219], v[46:49]
	v_mfma_f32_16x16x32_bf16 v[42:45], v[170:173], v[216:219], v[42:45]
	v_mfma_f32_16x16x32_bf16 v[30:33], v[158:161], v[224:227], v[30:33]
	v_mfma_f32_16x16x32_bf16 v[26:29], v[170:173], v[224:227], v[26:29]
	v_mfma_f32_16x16x32_bf16 v[14:17], v[158:161], v[232:235], v[14:17]
	v_mfma_f32_16x16x32_bf16 v[10:13], v[170:173], v[232:235], v[10:13]
	s_setprio 0
	s_setprio 1
	v_mfma_f32_16x16x32_bf16 v[54:57], v[174:177], v[190:193], v[54:57]
	v_mfma_f32_16x16x32_bf16 v[50:53], v[182:185], v[190:193], v[50:53]
	v_mfma_f32_16x16x32_bf16 v[38:41], v[174:177], v[198:201], v[38:41]
	v_mfma_f32_16x16x32_bf16 v[34:37], v[182:185], v[198:201], v[34:37]
	v_mfma_f32_16x16x32_bf16 v[22:25], v[174:177], v[220:223], v[22:25]
	v_mfma_f32_16x16x32_bf16 v[18:21], v[182:185], v[220:223], v[18:21]
	v_mfma_f32_16x16x32_bf16 v[6:9], v[174:177], v[228:231], v[6:9]
	v_mfma_f32_16x16x32_bf16 v[2:5], v[182:185], v[228:231], v[2:5]
	v_mfma_f32_16x16x32_bf16 v[54:57], v[178:181], v[194:197], v[54:57]
	v_mfma_f32_16x16x32_bf16 v[50:53], v[186:189], v[194:197], v[50:53]
	v_mfma_f32_16x16x32_bf16 v[38:41], v[178:181], v[216:219], v[38:41]
	v_mfma_f32_16x16x32_bf16 v[34:37], v[186:189], v[216:219], v[34:37]
	v_mfma_f32_16x16x32_bf16 v[22:25], v[178:181], v[224:227], v[22:25]
	v_mfma_f32_16x16x32_bf16 v[18:21], v[186:189], v[224:227], v[18:21]
	v_mfma_f32_16x16x32_bf16 v[6:9], v[178:181], v[232:235], v[6:9]
	v_mfma_f32_16x16x32_bf16 v[2:5], v[186:189], v[232:235], v[2:5]
	s_setprio 0
	s_barrier
	s_add_i32 s59, s59, 2
	s_add_u32 s57, s57, 0x100
	s_addc_u32 s58, s58, 0
	s_add_u32 s8, s8, 0x100
	s_addc_u32 s9, s9, 0
	s_cmp_gt_u32 s59, 29
	s_cbranch_scc0 .LBB0_140
	s_and_b64 vcc, exec, s[20:21]
	s_cbranch_vccz .LBB0_143
	s_barrier
.LBB0_143:
	s_add_i32 s0, s55, -12
	s_cmp_lt_u32 s0, 6
	v_lshl_add_u32 v170, s56, 8, v166
	v_mov_b32_e32 v160, 1.0
	v_mov_b32_e32 v161, 0
	s_cselect_b64 s[10:11], -1, 0
	s_cmp_gt_u32 s0, 5
	v_mov_b32_e32 v165, 0
	v_mov_b32_e32 v131, 0
	v_mov_b32_e32 v163, 0
	v_mov_b32_e32 v133, 0
	v_mov_b32_e32 v164, 1.0
	v_mov_b32_e32 v130, 1.0
	v_mov_b32_e32 v162, 1.0
	v_mov_b32_e32 v132, 1.0
	s_cbranch_scc1 .Lepi_fast
	v_mov_b32_e32 v245, 0
	v_lshl_or_b32 v158, s55, 8, v168
	v_ashrrev_i32_e32 v159, 31, v158
	v_lshlrev_b32_e32 v244, 8, v170
	v_and_b32_e32 v244, 0x7ff00, v244
	v_lshl_add_u64 v[246:247], v[142:143], 0, v[244:245]
	global_load_dwordx4 v[184:187], v[246:247], off
	v_lshl_add_u64 v[246:247], v[144:145], 0, v[244:245]
	global_load_dwordx4 v[188:191], v[246:247], off
	v_add_u32_e32 v244, 16, v170
	v_lshlrev_b32_e32 v244, 8, v244
	v_and_b32_e32 v244, 0x7ff00, v244
	v_lshl_add_u64 v[246:247], v[142:143], 0, v[244:245]
	global_load_dwordx4 v[192:195], v[246:247], off
	v_lshl_add_u64 v[246:247], v[144:145], 0, v[244:245]
	global_load_dwordx4 v[196:199], v[246:247], off
	v_add_u32_e32 v244, 32, v170
	v_lshlrev_b32_e32 v244, 8, v244
	v_and_b32_e32 v244, 0x7ff00, v244
	v_lshl_add_u64 v[246:247], v[142:143], 0, v[244:245]
	global_load_dwordx4 v[200:203], v[246:247], off
	v_lshl_add_u64 v[246:247], v[144:145], 0, v[244:245]
	global_load_dwordx4 v[216:219], v[246:247], off
	v_add_u32_e32 v244, 48, v170
	v_lshlrev_b32_e32 v244, 8, v244
	v_and_b32_e32 v244, 0x7ff00, v244
	v_lshl_add_u64 v[246:247], v[142:143], 0, v[244:245]
	global_load_dwordx4 v[220:223], v[246:247], off
	v_lshl_add_u64 v[246:247], v[144:145], 0, v[244:245]
	global_load_dwordx4 v[224:227], v[246:247], off
	v_add_u32_e32 v244, 0x80, v170
	v_lshlrev_b32_e32 v244, 8, v244
	v_and_b32_e32 v244, 0x7ff00, v244
	v_lshl_add_u64 v[246:247], v[142:143], 0, v[244:245]
	global_load_dwordx4 v[228:231], v[246:247], off
	v_lshl_add_u64 v[246:247], v[144:145], 0, v[244:245]
	global_load_dwordx4 v[232:235], v[246:247], off
	v_add_u32_e32 v244, 0x90, v170
	v_lshlrev_b32_e32 v244, 8, v244
	v_and_b32_e32 v244, 0x7ff00, v244
	v_lshl_add_u64 v[246:247], v[142:143], 0, v[244:245]
	global_load_dwordx4 v[236:239], v[246:247], off
	v_lshl_add_u64 v[246:247], v[144:145], 0, v[244:245]
	global_load_dwordx4 v[240:243], v[246:247], off
	s_waitcnt vmcnt(10)
	v_mov_b64_e32 v[182:183], s[12:13]
	v_mad_i64_i32 v[182:183], s[0:1], v170, s43, v[182:183]
	v_lshl_add_u64 v[182:183], v[158:159], 1, v[182:183]
	v_pk_mul_f32 v[160:161], v[126:127], v[188:189] op_sel:[0,0] op_sel_hi:[1,0]
	v_pk_fma_f32 v[126:127], v[126:127], v[184:185], v[160:161] op_sel:[1,0,0] op_sel_hi:[0,0,1] neg_lo:[0,1,0]
	v_pk_mul_f32 v[162:163], v[128:129], v[188:189] op_sel:[0,1] op_sel_hi:[1,1]
	v_pk_fma_f32 v[128:129], v[128:129], v[184:185], v[162:163] op_sel:[1,1,0] op_sel_hi:[0,1,1] neg_lo:[0,1,0]
	v_pk_mul_f32 v[164:165], v[122:123], v[190:191] op_sel:[0,0] op_sel_hi:[1,0]
	v_pk_fma_f32 v[122:123], v[122:123], v[186:187], v[164:165] op_sel:[1,0,0] op_sel_hi:[0,0,1] neg_lo:[0,1,0]
	v_pk_mul_f32 v[180:181], v[124:125], v[190:191] op_sel:[0,1] op_sel_hi:[1,1]
	v_pk_fma_f32 v[124:125], v[124:125], v[186:187], v[180:181] op_sel:[1,1,0] op_sel_hi:[0,1,1] neg_lo:[0,1,0]
	v_cvt_pk_bf16_f32 v172, v126, v127
	v_cvt_pk_bf16_f32 v173, v128, v129
	v_cvt_pk_bf16_f32 v174, v122, v123
	v_cvt_pk_bf16_f32 v175, v124, v125
	v_mov_b32_e32 v126, 0
	v_mov_b32_e32 v127, 0
	v_mov_b32_e32 v128, 0
	v_mov_b32_e32 v129, 0
	v_mov_b32_e32 v122, 0
	v_mov_b32_e32 v123, 0
	v_mov_b32_e32 v124, 0
	v_mov_b32_e32 v125, 0
	global_store_dwordx4 v[182:183], v[172:175], off sc1 nt
	v_pk_mul_f32 v[160:161], v[118:119], v[188:189] op_sel:[0,0] op_sel_hi:[1,0]
	v_pk_fma_f32 v[118:119], v[118:119], v[184:185], v[160:161] op_sel:[1,0,0] op_sel_hi:[0,0,1] neg_lo:[0,1,0]
	v_pk_mul_f32 v[162:163], v[120:121], v[188:189] op_sel:[0,1] op_sel_hi:[1,1]
	v_pk_fma_f32 v[120:121], v[120:121], v[184:185], v[162:163] op_sel:[1,1,0] op_sel_hi:[0,1,1] neg_lo:[0,1,0]
	v_pk_mul_f32 v[164:165], v[114:115], v[190:191] op_sel:[0,0] op_sel_hi:[1,0]
	v_pk_fma_f32 v[114:115], v[114:115], v[186:187], v[164:165] op_sel:[1,0,0] op_sel_hi:[0,0,1] neg_lo:[0,1,0]
	v_pk_mul_f32 v[180:181], v[116:117], v[190:191] op_sel:[0,1] op_sel_hi:[1,1]
	v_pk_fma_f32 v[116:117], v[116:117], v[186:187], v[180:181] op_sel:[1,1,0] op_sel_hi:[0,1,1] neg_lo:[0,1,0]
	v_cvt_pk_bf16_f32 v176, v118, v119
	v_cvt_pk_bf16_f32 v177, v120, v121
	v_cvt_pk_bf16_f32 v178, v114, v115
	v_cvt_pk_bf16_f32 v179, v116, v117
	v_mov_b32_e32 v118, 0
	v_mov_b32_e32 v119, 0
	v_mov_b32_e32 v120, 0
	v_mov_b32_e32 v121, 0
	v_mov_b32_e32 v114, 0
	v_mov_b32_e32 v115, 0
	v_mov_b32_e32 v116, 0
	v_mov_b32_e32 v117, 0
	global_store_dwordx4 v[182:183], v[176:179], off offset:256 sc1 nt
	s_waitcnt vmcnt(10)
	v_mov_b64_e32 v[182:183], s[12:13]
	v_add_u32_e32 v181, 16, v170
	v_mad_i64_i32 v[182:183], s[0:1], v181, s43, v[182:183]
	v_lshl_add_u64 v[182:183], v[158:159], 1, v[182:183]
	v_pk_mul_f32 v[160:161], v[110:111], v[196:197] op_sel:[0,0] op_sel_hi:[1,0]
	v_pk_fma_f32 v[110:111], v[110:111], v[192:193], v[160:161] op_sel:[1,0,0] op_sel_hi:[0,0,1] neg_lo:[0,1,0]
	v_pk_mul_f32 v[162:163], v[112:113], v[196:197] op_sel:[0,1] op_sel_hi:[1,1]
	v_pk_fma_f32 v[112:113], v[112:113], v[192:193], v[162:163] op_sel:[1,1,0] op_sel_hi:[0,1,1] neg_lo:[0,1,0]
	v_pk_mul_f32 v[164:165], v[106:107], v[198:199] op_sel:[0,0] op_sel_hi:[1,0]
	v_pk_fma_f32 v[106:107], v[106:107], v[194:195], v[164:165] op_sel:[1,0,0] op_sel_hi:[0,0,1] neg_lo:[0,1,0]
	v_pk_mul_f32 v[180:181], v[108:109], v[198:199] op_sel:[0,1] op_sel_hi:[1,1]
	v_pk_fma_f32 v[108:109], v[108:109], v[194:195], v[180:181] op_sel:[1,1,0] op_sel_hi:[0,1,1] neg_lo:[0,1,0]
	v_cvt_pk_bf16_f32 v172, v110, v111
	v_cvt_pk_bf16_f32 v173, v112, v113
	v_cvt_pk_bf16_f32 v174, v106, v107
	v_cvt_pk_bf16_f32 v175, v108, v109
	v_mov_b32_e32 v110, 0
	v_mov_b32_e32 v111, 0
	v_mov_b32_e32 v112, 0
	v_mov_b32_e32 v113, 0
	v_mov_b32_e32 v106, 0
	v_mov_b32_e32 v107, 0
	v_mov_b32_e32 v108, 0
	v_mov_b32_e32 v109, 0
	global_store_dwordx4 v[182:183], v[172:175], off sc1 nt
	v_pk_mul_f32 v[160:161], v[102:103], v[196:197] op_sel:[0,0] op_sel_hi:[1,0]
	v_pk_fma_f32 v[102:103], v[102:103], v[192:193], v[160:161] op_sel:[1,0,0] op_sel_hi:[0,0,1] neg_lo:[0,1,0]
	v_pk_mul_f32 v[162:163], v[104:105], v[196:197] op_sel:[0,1] op_sel_hi:[1,1]
	v_pk_fma_f32 v[104:105], v[104:105], v[192:193], v[162:163] op_sel:[1,1,0] op_sel_hi:[0,1,1] neg_lo:[0,1,0]
	v_pk_mul_f32 v[164:165], v[98:99], v[198:199] op_sel:[0,0] op_sel_hi:[1,0]
	v_pk_fma_f32 v[98:99], v[98:99], v[194:195], v[164:165] op_sel:[1,0,0] op_sel_hi:[0,0,1] neg_lo:[0,1,0]
	v_pk_mul_f32 v[180:181], v[100:101], v[198:199] op_sel:[0,1] op_sel_hi:[1,1]
	v_pk_fma_f32 v[100:101], v[100:101], v[194:195], v[180:181] op_sel:[1,1,0] op_sel_hi:[0,1,1] neg_lo:[0,1,0]
	v_cvt_pk_bf16_f32 v176, v102, v103
	v_cvt_pk_bf16_f32 v177, v104, v105
	v_cvt_pk_bf16_f32 v178, v98, v99
	v_cvt_pk_bf16_f32 v179, v100, v101
	v_mov_b32_e32 v102, 0
	v_mov_b32_e32 v103, 0
	v_mov_b32_e32 v104, 0
	v_mov_b32_e32 v105, 0
	v_mov_b32_e32 v98, 0
	v_mov_b32_e32 v99, 0
	v_mov_b32_e32 v100, 0
	v_mov_b32_e32 v101, 0
	global_store_dwordx4 v[182:183], v[176:179], off offset:256 sc1 nt
	v_add_u32_e32 v244, 0xa0, v170
	v_lshlrev_b32_e32 v244, 8, v244
	v_and_b32_e32 v244, 0x7ff00, v244
	v_lshl_add_u64 v[246:247], v[142:143], 0, v[244:245]
	global_load_dwordx4 v[184:187], v[246:247], off
	v_lshl_add_u64 v[246:247], v[144:145], 0, v[244:245]
	global_load_dwordx4 v[188:191], v[246:247], off
	v_add_u32_e32 v244, 0xb0, v170
	v_lshlrev_b32_e32 v244, 8, v244
	v_and_b32_e32 v244, 0x7ff00, v244
	v_lshl_add_u64 v[246:247], v[142:143], 0, v[244:245]
	global_load_dwordx4 v[192:195], v[246:247], off
	v_lshl_add_u64 v[246:247], v[144:145], 0, v[244:245]
	global_load_dwordx4 v[196:199], v[246:247], off
	s_waitcnt vmcnt(14)
	v_mov_b64_e32 v[182:183], s[12:13]
	v_add_u32_e32 v181, 32, v170
	v_mad_i64_i32 v[182:183], s[0:1], v181, s43, v[182:183]
	v_lshl_add_u64 v[182:183], v[158:159], 1, v[182:183]
	v_pk_mul_f32 v[160:161], v[94:95], v[216:217] op_sel:[0,0] op_sel_hi:[1,0]
	v_pk_fma_f32 v[94:95], v[94:95], v[200:201], v[160:161] op_sel:[1,0,0] op_sel_hi:[0,0,1] neg_lo:[0,1,0]
	v_pk_mul_f32 v[162:163], v[96:97], v[216:217] op_sel:[0,1] op_sel_hi:[1,1]
	v_pk_fma_f32 v[96:97], v[96:97], v[200:201], v[162:163] op_sel:[1,1,0] op_sel_hi:[0,1,1] neg_lo:[0,1,0]
	v_pk_mul_f32 v[164:165], v[90:91], v[218:219] op_sel:[0,0] op_sel_hi:[1,0]
	v_pk_fma_f32 v[90:91], v[90:91], v[202:203], v[164:165] op_sel:[1,0,0] op_sel_hi:[0,0,1] neg_lo:[0,1,0]
	v_pk_mul_f32 v[180:181], v[92:93], v[218:219] op_sel:[0,1] op_sel_hi:[1,1]
	v_pk_fma_f32 v[92:93], v[92:93], v[202:203], v[180:181] op_sel:[1,1,0] op_sel_hi:[0,1,1] neg_lo:[0,1,0]
	v_cvt_pk_bf16_f32 v172, v94, v95
	v_cvt_pk_bf16_f32 v173, v96, v97
	v_cvt_pk_bf16_f32 v174, v90, v91
	v_cvt_pk_bf16_f32 v175, v92, v93
	v_mov_b32_e32 v94, 0
	v_mov_b32_e32 v95, 0
	v_mov_b32_e32 v96, 0
	v_mov_b32_e32 v97, 0
	v_mov_b32_e32 v90, 0
	v_mov_b32_e32 v91, 0
	v_mov_b32_e32 v92, 0
	v_mov_b32_e32 v93, 0
	global_store_dwordx4 v[182:183], v[172:175], off sc1 nt
	v_pk_mul_f32 v[160:161], v[86:87], v[216:217] op_sel:[0,0] op_sel_hi:[1,0]
	v_pk_fma_f32 v[86:87], v[86:87], v[200:201], v[160:161] op_sel:[1,0,0] op_sel_hi:[0,0,1] neg_lo:[0,1,0]
	v_pk_mul_f32 v[162:163], v[88:89], v[216:217] op_sel:[0,1] op_sel_hi:[1,1]
	v_pk_fma_f32 v[88:89], v[88:89], v[200:201], v[162:163] op_sel:[1,1,0] op_sel_hi:[0,1,1] neg_lo:[0,1,0]
	v_pk_mul_f32 v[164:165], v[82:83], v[218:219] op_sel:[0,0] op_sel_hi:[1,0]
	v_pk_fma_f32 v[82:83], v[82:83], v[202:203], v[164:165] op_sel:[1,0,0] op_sel_hi:[0,0,1] neg_lo:[0,1,0]
	v_pk_mul_f32 v[180:181], v[84:85], v[218:219] op_sel:[0,1] op_sel_hi:[1,1]
	v_pk_fma_f32 v[84:85], v[84:85], v[202:203], v[180:181] op_sel:[1,1,0] op_sel_hi:[0,1,1] neg_lo:[0,1,0]
	v_cvt_pk_bf16_f32 v176, v86, v87
	v_cvt_pk_bf16_f32 v177, v88, v89
	v_cvt_pk_bf16_f32 v178, v82, v83
	v_cvt_pk_bf16_f32 v179, v84, v85
	v_mov_b32_e32 v86, 0
	v_mov_b32_e32 v87, 0
	v_mov_b32_e32 v88, 0
	v_mov_b32_e32 v89, 0
	v_mov_b32_e32 v82, 0
	v_mov_b32_e32 v83, 0
	v_mov_b32_e32 v84, 0
	v_mov_b32_e32 v85, 0
	global_store_dwordx4 v[182:183], v[176:179], off offset:256 sc1 nt
	s_waitcnt vmcnt(14)
	v_mov_b64_e32 v[182:183], s[12:13]
	v_add_u32_e32 v181, 48, v170
	v_mad_i64_i32 v[182:183], s[0:1], v181, s43, v[182:183]
	v_lshl_add_u64 v[182:183], v[158:159], 1, v[182:183]
	v_pk_mul_f32 v[160:161], v[78:79], v[224:225] op_sel:[0,0] op_sel_hi:[1,0]
	v_pk_fma_f32 v[78:79], v[78:79], v[220:221], v[160:161] op_sel:[1,0,0] op_sel_hi:[0,0,1] neg_lo:[0,1,0]
	v_pk_mul_f32 v[162:163], v[80:81], v[224:225] op_sel:[0,1] op_sel_hi:[1,1]
	v_pk_fma_f32 v[80:81], v[80:81], v[220:221], v[162:163] op_sel:[1,1,0] op_sel_hi:[0,1,1] neg_lo:[0,1,0]
	v_pk_mul_f32 v[164:165], v[74:75], v[226:227] op_sel:[0,0] op_sel_hi:[1,0]
	v_pk_fma_f32 v[74:75], v[74:75], v[222:223], v[164:165] op_sel:[1,0,0] op_sel_hi:[0,0,1] neg_lo:[0,1,0]
	v_pk_mul_f32 v[180:181], v[76:77], v[226:227] op_sel:[0,1] op_sel_hi:[1,1]
	v_pk_fma_f32 v[76:77], v[76:77], v[222:223], v[180:181] op_sel:[1,1,0] op_sel_hi:[0,1,1] neg_lo:[0,1,0]
	v_cvt_pk_bf16_f32 v172, v78, v79
	v_cvt_pk_bf16_f32 v173, v80, v81
	v_cvt_pk_bf16_f32 v174, v74, v75
	v_cvt_pk_bf16_f32 v175, v76, v77
	v_mov_b32_e32 v78, 0
	v_mov_b32_e32 v79, 0
	v_mov_b32_e32 v80, 0
	v_mov_b32_e32 v81, 0
	v_mov_b32_e32 v74, 0
	v_mov_b32_e32 v75, 0
	v_mov_b32_e32 v76, 0
	v_mov_b32_e32 v77, 0
	global_store_dwordx4 v[182:183], v[172:175], off sc1 nt
	v_pk_mul_f32 v[160:161], v[70:71], v[224:225] op_sel:[0,0] op_sel_hi:[1,0]
	v_pk_fma_f32 v[70:71], v[70:71], v[220:221], v[160:161] op_sel:[1,0,0] op_sel_hi:[0,0,1] neg_lo:[0,1,0]
	v_pk_mul_f32 v[162:163], v[72:73], v[224:225] op_sel:[0,1] op_sel_hi:[1,1]
	v_pk_fma_f32 v[72:73], v[72:73], v[220:221], v[162:163] op_sel:[1,1,0] op_sel_hi:[0,1,1] neg_lo:[0,1,0]
	v_pk_mul_f32 v[164:165], v[66:67], v[226:227] op_sel:[0,0] op_sel_hi:[1,0]
	v_pk_fma_f32 v[66:67], v[66:67], v[222:223], v[164:165] op_sel:[1,0,0] op_sel_hi:[0,0,1] neg_lo:[0,1,0]
	v_pk_mul_f32 v[180:181], v[68:69], v[226:227] op_sel:[0,1] op_sel_hi:[1,1]
	v_pk_fma_f32 v[68:69], v[68:69], v[222:223], v[180:181] op_sel:[1,1,0] op_sel_hi:[0,1,1] neg_lo:[0,1,0]
	v_cvt_pk_bf16_f32 v176, v70, v71
	v_cvt_pk_bf16_f32 v177, v72, v73
	v_cvt_pk_bf16_f32 v178, v66, v67
	v_cvt_pk_bf16_f32 v179, v68, v69
	v_mov_b32_e32 v70, 0
	v_mov_b32_e32 v71, 0
	v_mov_b32_e32 v72, 0
	v_mov_b32_e32 v73, 0
	v_mov_b32_e32 v66, 0
	v_mov_b32_e32 v67, 0
	v_mov_b32_e32 v68, 0
	v_mov_b32_e32 v69, 0
	global_store_dwordx4 v[182:183], v[176:179], off offset:256 sc1 nt
	s_waitcnt vmcnt(14)
	v_mov_b64_e32 v[182:183], s[12:13]
	v_add_u32_e32 v181, 0x80, v170
	v_mad_i64_i32 v[182:183], s[0:1], v181, s43, v[182:183]
	v_lshl_add_u64 v[182:183], v[158:159], 1, v[182:183]
	v_pk_mul_f32 v[160:161], v[62:63], v[232:233] op_sel:[0,0] op_sel_hi:[1,0]
	v_pk_fma_f32 v[62:63], v[62:63], v[228:229], v[160:161] op_sel:[1,0,0] op_sel_hi:[0,0,1] neg_lo:[0,1,0]
	v_pk_mul_f32 v[162:163], v[64:65], v[232:233] op_sel:[0,1] op_sel_hi:[1,1]
	v_pk_fma_f32 v[64:65], v[64:65], v[228:229], v[162:163] op_sel:[1,1,0] op_sel_hi:[0,1,1] neg_lo:[0,1,0]
	v_pk_mul_f32 v[164:165], v[58:59], v[234:235] op_sel:[0,0] op_sel_hi:[1,0]
	v_pk_fma_f32 v[58:59], v[58:59], v[230:231], v[164:165] op_sel:[1,0,0] op_sel_hi:[0,0,1] neg_lo:[0,1,0]
	v_pk_mul_f32 v[180:181], v[60:61], v[234:235] op_sel:[0,1] op_sel_hi:[1,1]
	v_pk_fma_f32 v[60:61], v[60:61], v[230:231], v[180:181] op_sel:[1,1,0] op_sel_hi:[0,1,1] neg_lo:[0,1,0]
	v_cvt_pk_bf16_f32 v172, v62, v63
	v_cvt_pk_bf16_f32 v173, v64, v65
	v_cvt_pk_bf16_f32 v174, v58, v59
	v_cvt_pk_bf16_f32 v175, v60, v61
	v_mov_b32_e32 v62, 0
	v_mov_b32_e32 v63, 0
	v_mov_b32_e32 v64, 0
	v_mov_b32_e32 v65, 0
	v_mov_b32_e32 v58, 0
	v_mov_b32_e32 v59, 0
	v_mov_b32_e32 v60, 0
	v_mov_b32_e32 v61, 0
	global_store_dwordx4 v[182:183], v[172:175], off sc1 nt
	v_pk_mul_f32 v[160:161], v[54:55], v[232:233] op_sel:[0,0] op_sel_hi:[1,0]
	v_pk_fma_f32 v[54:55], v[54:55], v[228:229], v[160:161] op_sel:[1,0,0] op_sel_hi:[0,0,1] neg_lo:[0,1,0]
	v_pk_mul_f32 v[162:163], v[56:57], v[232:233] op_sel:[0,1] op_sel_hi:[1,1]
	v_pk_fma_f32 v[56:57], v[56:57], v[228:229], v[162:163] op_sel:[1,1,0] op_sel_hi:[0,1,1] neg_lo:[0,1,0]
	v_pk_mul_f32 v[164:165], v[50:51], v[234:235] op_sel:[0,0] op_sel_hi:[1,0]
	v_pk_fma_f32 v[50:51], v[50:51], v[230:231], v[164:165] op_sel:[1,0,0] op_sel_hi:[0,0,1] neg_lo:[0,1,0]
	v_pk_mul_f32 v[180:181], v[52:53], v[234:235] op_sel:[0,1] op_sel_hi:[1,1]
	v_pk_fma_f32 v[52:53], v[52:53], v[230:231], v[180:181] op_sel:[1,1,0] op_sel_hi:[0,1,1] neg_lo:[0,1,0]
	v_cvt_pk_bf16_f32 v176, v54, v55
	v_cvt_pk_bf16_f32 v177, v56, v57
	v_cvt_pk_bf16_f32 v178, v50, v51
	v_cvt_pk_bf16_f32 v179, v52, v53
	v_mov_b32_e32 v54, 0
	v_mov_b32_e32 v55, 0
	v_mov_b32_e32 v56, 0
	v_mov_b32_e32 v57, 0
	v_mov_b32_e32 v50, 0
	v_mov_b32_e32 v51, 0
	v_mov_b32_e32 v52, 0
	v_mov_b32_e32 v53, 0
	global_store_dwordx4 v[182:183], v[176:179], off offset:256 sc1 nt
	s_waitcnt vmcnt(14)
	v_mov_b64_e32 v[182:183], s[12:13]
	v_add_u32_e32 v181, 0x90, v170
	v_mad_i64_i32 v[182:183], s[0:1], v181, s43, v[182:183]
	v_lshl_add_u64 v[182:183], v[158:159], 1, v[182:183]
	v_pk_mul_f32 v[160:161], v[46:47], v[240:241] op_sel:[0,0] op_sel_hi:[1,0]
	v_pk_fma_f32 v[46:47], v[46:47], v[236:237], v[160:161] op_sel:[1,0,0] op_sel_hi:[0,0,1] neg_lo:[0,1,0]
	v_pk_mul_f32 v[162:163], v[48:49], v[240:241] op_sel:[0,1] op_sel_hi:[1,1]
	v_pk_fma_f32 v[48:49], v[48:49], v[236:237], v[162:163] op_sel:[1,1,0] op_sel_hi:[0,1,1] neg_lo:[0,1,0]
	v_pk_mul_f32 v[164:165], v[42:43], v[242:243] op_sel:[0,0] op_sel_hi:[1,0]
	v_pk_fma_f32 v[42:43], v[42:43], v[238:239], v[164:165] op_sel:[1,0,0] op_sel_hi:[0,0,1] neg_lo:[0,1,0]
	v_pk_mul_f32 v[180:181], v[44:45], v[242:243] op_sel:[0,1] op_sel_hi:[1,1]
	v_pk_fma_f32 v[44:45], v[44:45], v[238:239], v[180:181] op_sel:[1,1,0] op_sel_hi:[0,1,1] neg_lo:[0,1,0]
	v_cvt_pk_bf16_f32 v172, v46, v47
	v_cvt_pk_bf16_f32 v173, v48, v49
	v_cvt_pk_bf16_f32 v174, v42, v43
	v_cvt_pk_bf16_f32 v175, v44, v45
	v_mov_b32_e32 v46, 0
	v_mov_b32_e32 v47, 0
	v_mov_b32_e32 v48, 0
	v_mov_b32_e32 v49, 0
	v_mov_b32_e32 v42, 0
	v_mov_b32_e32 v43, 0
	v_mov_b32_e32 v44, 0
	v_mov_b32_e32 v45, 0
	global_store_dwordx4 v[182:183], v[172:175], off sc1 nt
	v_pk_mul_f32 v[160:161], v[38:39], v[240:241] op_sel:[0,0] op_sel_hi:[1,0]
	v_pk_fma_f32 v[38:39], v[38:39], v[236:237], v[160:161] op_sel:[1,0,0] op_sel_hi:[0,0,1] neg_lo:[0,1,0]
	v_pk_mul_f32 v[162:163], v[40:41], v[240:241] op_sel:[0,1] op_sel_hi:[1,1]
	v_pk_fma_f32 v[40:41], v[40:41], v[236:237], v[162:163] op_sel:[1,1,0] op_sel_hi:[0,1,1] neg_lo:[0,1,0]
	v_pk_mul_f32 v[164:165], v[34:35], v[242:243] op_sel:[0,0] op_sel_hi:[1,0]
	v_pk_fma_f32 v[34:35], v[34:35], v[238:239], v[164:165] op_sel:[1,0,0] op_sel_hi:[0,0,1] neg_lo:[0,1,0]
	v_pk_mul_f32 v[180:181], v[36:37], v[242:243] op_sel:[0,1] op_sel_hi:[1,1]
	v_pk_fma_f32 v[36:37], v[36:37], v[238:239], v[180:181] op_sel:[1,1,0] op_sel_hi:[0,1,1] neg_lo:[0,1,0]
	v_cvt_pk_bf16_f32 v176, v38, v39
	v_cvt_pk_bf16_f32 v177, v40, v41
	v_cvt_pk_bf16_f32 v178, v34, v35
	v_cvt_pk_bf16_f32 v179, v36, v37
	v_mov_b32_e32 v38, 0
	v_mov_b32_e32 v39, 0
	v_mov_b32_e32 v40, 0
	v_mov_b32_e32 v41, 0
	v_mov_b32_e32 v34, 0
	v_mov_b32_e32 v35, 0
	v_mov_b32_e32 v36, 0
	v_mov_b32_e32 v37, 0
	global_store_dwordx4 v[182:183], v[176:179], off offset:256 sc1 nt
	s_waitcnt vmcnt(10)
	v_mov_b64_e32 v[182:183], s[12:13]
	v_add_u32_e32 v181, 0xa0, v170
	v_mad_i64_i32 v[182:183], s[0:1], v181, s43, v[182:183]
	v_lshl_add_u64 v[182:183], v[158:159], 1, v[182:183]
	v_pk_mul_f32 v[160:161], v[30:31], v[188:189] op_sel:[0,0] op_sel_hi:[1,0]
	v_pk_fma_f32 v[30:31], v[30:31], v[184:185], v[160:161] op_sel:[1,0,0] op_sel_hi:[0,0,1] neg_lo:[0,1,0]
	v_pk_mul_f32 v[162:163], v[32:33], v[188:189] op_sel:[0,1] op_sel_hi:[1,1]
	v_pk_fma_f32 v[32:33], v[32:33], v[184:185], v[162:163] op_sel:[1,1,0] op_sel_hi:[0,1,1] neg_lo:[0,1,0]
	v_pk_mul_f32 v[164:165], v[26:27], v[190:191] op_sel:[0,0] op_sel_hi:[1,0]
	v_pk_fma_f32 v[26:27], v[26:27], v[186:187], v[164:165] op_sel:[1,0,0] op_sel_hi:[0,0,1] neg_lo:[0,1,0]
	v_pk_mul_f32 v[180:181], v[28:29], v[190:191] op_sel:[0,1] op_sel_hi:[1,1]
	v_pk_fma_f32 v[28:29], v[28:29], v[186:187], v[180:181] op_sel:[1,1,0] op_sel_hi:[0,1,1] neg_lo:[0,1,0]
	v_cvt_pk_bf16_f32 v172, v30, v31
	v_cvt_pk_bf16_f32 v173, v32, v33
	v_cvt_pk_bf16_f32 v174, v26, v27
	v_cvt_pk_bf16_f32 v175, v28, v29
	v_mov_b32_e32 v30, 0
	v_mov_b32_e32 v31, 0
	v_mov_b32_e32 v32, 0
	v_mov_b32_e32 v33, 0
	v_mov_b32_e32 v26, 0
	v_mov_b32_e32 v27, 0
	v_mov_b32_e32 v28, 0
	v_mov_b32_e32 v29, 0
	global_store_dwordx4 v[182:183], v[172:175], off sc1 nt
	v_pk_mul_f32 v[160:161], v[22:23], v[188:189] op_sel:[0,0] op_sel_hi:[1,0]
	v_pk_fma_f32 v[22:23], v[22:23], v[184:185], v[160:161] op_sel:[1,0,0] op_sel_hi:[0,0,1] neg_lo:[0,1,0]
	v_pk_mul_f32 v[162:163], v[24:25], v[188:189] op_sel:[0,1] op_sel_hi:[1,1]
	v_pk_fma_f32 v[24:25], v[24:25], v[184:185], v[162:163] op_sel:[1,1,0] op_sel_hi:[0,1,1] neg_lo:[0,1,0]
	v_pk_mul_f32 v[164:165], v[18:19], v[190:191] op_sel:[0,0] op_sel_hi:[1,0]
	v_pk_fma_f32 v[18:19], v[18:19], v[186:187], v[164:165] op_sel:[1,0,0] op_sel_hi:[0,0,1] neg_lo:[0,1,0]
	v_pk_mul_f32 v[180:181], v[20:21], v[190:191] op_sel:[0,1] op_sel_hi:[1,1]
	v_pk_fma_f32 v[20:21], v[20:21], v[186:187], v[180:181] op_sel:[1,1,0] op_sel_hi:[0,1,1] neg_lo:[0,1,0]
	v_cvt_pk_bf16_f32 v176, v22, v23
	v_cvt_pk_bf16_f32 v177, v24, v25
	v_cvt_pk_bf16_f32 v178, v18, v19
	v_cvt_pk_bf16_f32 v179, v20, v21
	v_mov_b32_e32 v22, 0
	v_mov_b32_e32 v23, 0
	v_mov_b32_e32 v24, 0
	v_mov_b32_e32 v25, 0
	v_mov_b32_e32 v18, 0
	v_mov_b32_e32 v19, 0
	v_mov_b32_e32 v20, 0
	v_mov_b32_e32 v21, 0
	global_store_dwordx4 v[182:183], v[176:179], off offset:256 sc1 nt
	s_waitcnt vmcnt(10)
	v_mov_b64_e32 v[182:183], s[12:13]
	v_add_u32_e32 v181, 0xb0, v170
	v_mad_i64_i32 v[182:183], s[0:1], v181, s43, v[182:183]
	v_lshl_add_u64 v[182:183], v[158:159], 1, v[182:183]
	v_pk_mul_f32 v[160:161], v[14:15], v[196:197] op_sel:[0,0] op_sel_hi:[1,0]
	v_pk_fma_f32 v[14:15], v[14:15], v[192:193], v[160:161] op_sel:[1,0,0] op_sel_hi:[0,0,1] neg_lo:[0,1,0]
	v_pk_mul_f32 v[162:163], v[16:17], v[196:197] op_sel:[0,1] op_sel_hi:[1,1]
	v_pk_fma_f32 v[16:17], v[16:17], v[192:193], v[162:163] op_sel:[1,1,0] op_sel_hi:[0,1,1] neg_lo:[0,1,0]
	v_pk_mul_f32 v[164:165], v[10:11], v[198:199] op_sel:[0,0] op_sel_hi:[1,0]
	v_pk_fma_f32 v[10:11], v[10:11], v[194:195], v[164:165] op_sel:[1,0,0] op_sel_hi:[0,0,1] neg_lo:[0,1,0]
	v_pk_mul_f32 v[180:181], v[12:13], v[198:199] op_sel:[0,1] op_sel_hi:[1,1]
	v_pk_fma_f32 v[12:13], v[12:13], v[194:195], v[180:181] op_sel:[1,1,0] op_sel_hi:[0,1,1] neg_lo:[0,1,0]
	v_cvt_pk_bf16_f32 v172, v14, v15
	v_cvt_pk_bf16_f32 v173, v16, v17
	v_cvt_pk_bf16_f32 v174, v10, v11
	v_cvt_pk_bf16_f32 v175, v12, v13
	v_mov_b32_e32 v14, 0
	v_mov_b32_e32 v15, 0
	v_mov_b32_e32 v16, 0
	v_mov_b32_e32 v17, 0
	v_mov_b32_e32 v10, 0
	v_mov_b32_e32 v11, 0
	v_mov_b32_e32 v12, 0
	v_mov_b32_e32 v13, 0
	global_store_dwordx4 v[182:183], v[172:175], off sc1 nt
	v_pk_mul_f32 v[160:161], v[6:7], v[196:197] op_sel:[0,0] op_sel_hi:[1,0]
	v_pk_fma_f32 v[6:7], v[6:7], v[192:193], v[160:161] op_sel:[1,0,0] op_sel_hi:[0,0,1] neg_lo:[0,1,0]
	v_pk_mul_f32 v[162:163], v[8:9], v[196:197] op_sel:[0,1] op_sel_hi:[1,1]
	v_pk_fma_f32 v[8:9], v[8:9], v[192:193], v[162:163] op_sel:[1,1,0] op_sel_hi:[0,1,1] neg_lo:[0,1,0]
	v_pk_mul_f32 v[164:165], v[2:3], v[198:199] op_sel:[0,0] op_sel_hi:[1,0]
	v_pk_fma_f32 v[2:3], v[2:3], v[194:195], v[164:165] op_sel:[1,0,0] op_sel_hi:[0,0,1] neg_lo:[0,1,0]
	v_pk_mul_f32 v[180:181], v[4:5], v[198:199] op_sel:[0,1] op_sel_hi:[1,1]
	v_pk_fma_f32 v[4:5], v[4:5], v[194:195], v[180:181] op_sel:[1,1,0] op_sel_hi:[0,1,1] neg_lo:[0,1,0]
	v_cvt_pk_bf16_f32 v176, v6, v7
	v_cvt_pk_bf16_f32 v177, v8, v9
	v_cvt_pk_bf16_f32 v178, v2, v3
	v_cvt_pk_bf16_f32 v179, v4, v5
	v_mov_b32_e32 v6, 0
	v_mov_b32_e32 v7, 0
	v_mov_b32_e32 v8, 0
	v_mov_b32_e32 v9, 0
	v_mov_b32_e32 v2, 0
	v_mov_b32_e32 v3, 0
	v_mov_b32_e32 v4, 0
	v_mov_b32_e32 v5, 0
	global_store_dwordx4 v[182:183], v[176:179], off offset:256 sc1 nt

.Lepi_fast:
	v_lshl_or_b32 v158, s55, 8, v168
	v_ashrrev_i32_e32 v159, 31, v158
	v_mov_b64_e32 v[172:173], s[12:13]
	v_mad_i64_i32 v[172:173], s[0:1], v170, s43, v[172:173]
	v_cvt_pk_bf16_f32 v126, v126, v127
	v_cvt_pk_bf16_f32 v127, v128, v129
	v_cvt_pk_bf16_f32 v128, v122, v123
	v_cvt_pk_bf16_f32 v129, v124, v125
	v_lshl_add_u64 v[172:173], v[158:159], 1, v[172:173]
	v_cvt_pk_bf16_f32 v118, v118, v119
	v_cvt_pk_bf16_f32 v119, v120, v121
	v_cvt_pk_bf16_f32 v120, v114, v115
	v_cvt_pk_bf16_f32 v121, v116, v117
	global_store_dwordx4 v[172:173], v[126:129], off sc1 nt
	global_store_dwordx4 v[172:173], v[118:121], off offset:256 sc1 nt
	v_add_u32_e32 v174, 16, v170
	v_mov_b64_e32 v[172:173], s[12:13]
	v_mad_i64_i32 v[172:173], s[0:1], v174, s43, v[172:173]
	v_mov_b32_e32 v114, 0
	v_mov_b32_e32 v115, 0
	v_mov_b32_e32 v116, 0
	v_mov_b32_e32 v117, 0
	v_mov_b32_e32 v118, 0
	v_mov_b32_e32 v119, 0
	v_mov_b32_e32 v120, 0
	v_mov_b32_e32 v121, 0
	v_mov_b32_e32 v122, 0
	v_mov_b32_e32 v123, 0
	v_mov_b32_e32 v124, 0
	v_mov_b32_e32 v125, 0
	v_mov_b32_e32 v126, 0
	v_mov_b32_e32 v127, 0
	v_mov_b32_e32 v128, 0
	v_mov_b32_e32 v129, 0
	v_cvt_pk_bf16_f32 v110, v110, v111
	v_cvt_pk_bf16_f32 v111, v112, v113
	v_cvt_pk_bf16_f32 v112, v106, v107
	v_cvt_pk_bf16_f32 v113, v108, v109
	v_lshl_add_u64 v[172:173], v[158:159], 1, v[172:173]
	v_cvt_pk_bf16_f32 v102, v102, v103
	v_cvt_pk_bf16_f32 v103, v104, v105
	v_cvt_pk_bf16_f32 v104, v98, v99
	v_cvt_pk_bf16_f32 v105, v100, v101
	global_store_dwordx4 v[172:173], v[110:113], off sc1 nt
	global_store_dwordx4 v[172:173], v[102:105], off offset:256 sc1 nt
	v_add_u32_e32 v174, 32, v170
	v_mov_b64_e32 v[172:173], s[12:13]
	v_mad_i64_i32 v[172:173], s[0:1], v174, s43, v[172:173]
	v_mov_b32_e32 v98, 0
	v_mov_b32_e32 v99, 0
	v_mov_b32_e32 v100, 0
	v_mov_b32_e32 v101, 0
	v_mov_b32_e32 v102, 0
	v_mov_b32_e32 v103, 0
	v_mov_b32_e32 v104, 0
	v_mov_b32_e32 v105, 0
	v_mov_b32_e32 v106, 0
	v_mov_b32_e32 v107, 0
	v_mov_b32_e32 v108, 0
	v_mov_b32_e32 v109, 0
	v_mov_b32_e32 v110, 0
	v_mov_b32_e32 v111, 0
	v_mov_b32_e32 v112, 0
	v_mov_b32_e32 v113, 0
	v_cvt_pk_bf16_f32 v94, v94, v95
	v_cvt_pk_bf16_f32 v95, v96, v97
	v_cvt_pk_bf16_f32 v96, v90, v91
	v_cvt_pk_bf16_f32 v97, v92, v93
	v_lshl_add_u64 v[172:173], v[158:159], 1, v[172:173]
	v_cvt_pk_bf16_f32 v86, v86, v87
	v_cvt_pk_bf16_f32 v87, v88, v89
	v_cvt_pk_bf16_f32 v88, v82, v83
	v_cvt_pk_bf16_f32 v89, v84, v85
	global_store_dwordx4 v[172:173], v[94:97], off sc1 nt
	global_store_dwordx4 v[172:173], v[86:89], off offset:256 sc1 nt
	v_add_u32_e32 v174, 48, v170
	v_mov_b64_e32 v[172:173], s[12:13]
	v_mad_i64_i32 v[172:173], s[0:1], v174, s43, v[172:173]
	v_mov_b32_e32 v82, 0
	v_mov_b32_e32 v83, 0
	v_mov_b32_e32 v84, 0
	v_mov_b32_e32 v85, 0
	v_mov_b32_e32 v86, 0
	v_mov_b32_e32 v87, 0
	v_mov_b32_e32 v88, 0
	v_mov_b32_e32 v89, 0
	v_mov_b32_e32 v90, 0
	v_mov_b32_e32 v91, 0
	v_mov_b32_e32 v92, 0
	v_mov_b32_e32 v93, 0
	v_mov_b32_e32 v94, 0
	v_mov_b32_e32 v95, 0
	v_mov_b32_e32 v96, 0
	v_mov_b32_e32 v97, 0
	v_cvt_pk_bf16_f32 v78, v78, v79
	v_cvt_pk_bf16_f32 v79, v80, v81
	v_cvt_pk_bf16_f32 v80, v74, v75
	v_cvt_pk_bf16_f32 v81, v76, v77
	v_lshl_add_u64 v[172:173], v[158:159], 1, v[172:173]
	v_cvt_pk_bf16_f32 v70, v70, v71
	v_cvt_pk_bf16_f32 v71, v72, v73
	v_cvt_pk_bf16_f32 v72, v66, v67
	v_cvt_pk_bf16_f32 v73, v68, v69
	global_store_dwordx4 v[172:173], v[78:81], off sc1 nt
	global_store_dwordx4 v[172:173], v[70:73], off offset:256 sc1 nt
	v_add_u32_e32 v174, 0x80, v170
	v_mov_b64_e32 v[172:173], s[12:13]
	v_mad_i64_i32 v[172:173], s[0:1], v174, s43, v[172:173]
	v_mov_b32_e32 v66, 0
	v_mov_b32_e32 v67, 0
	v_mov_b32_e32 v68, 0
	v_mov_b32_e32 v69, 0
	v_mov_b32_e32 v70, 0
	v_mov_b32_e32 v71, 0
	v_mov_b32_e32 v72, 0
	v_mov_b32_e32 v73, 0
	v_mov_b32_e32 v74, 0
	v_mov_b32_e32 v75, 0
	v_mov_b32_e32 v76, 0
	v_mov_b32_e32 v77, 0
	v_mov_b32_e32 v78, 0
	v_mov_b32_e32 v79, 0
	v_mov_b32_e32 v80, 0
	v_mov_b32_e32 v81, 0
	v_cvt_pk_bf16_f32 v62, v62, v63
	v_cvt_pk_bf16_f32 v63, v64, v65
	v_cvt_pk_bf16_f32 v64, v58, v59
	v_cvt_pk_bf16_f32 v65, v60, v61
	v_lshl_add_u64 v[172:173], v[158:159], 1, v[172:173]
	v_cvt_pk_bf16_f32 v54, v54, v55
	v_cvt_pk_bf16_f32 v55, v56, v57
	v_cvt_pk_bf16_f32 v56, v50, v51
	v_cvt_pk_bf16_f32 v57, v52, v53
	global_store_dwordx4 v[172:173], v[62:65], off sc1 nt
	global_store_dwordx4 v[172:173], v[54:57], off offset:256 sc1 nt
	v_add_u32_e32 v174, 0x90, v170
	v_mov_b64_e32 v[172:173], s[12:13]
	v_mad_i64_i32 v[172:173], s[0:1], v174, s43, v[172:173]
	v_mov_b32_e32 v50, 0
	v_mov_b32_e32 v51, 0
	v_mov_b32_e32 v52, 0
	v_mov_b32_e32 v53, 0
	v_mov_b32_e32 v54, 0
	v_mov_b32_e32 v55, 0
	v_mov_b32_e32 v56, 0
	v_mov_b32_e32 v57, 0
	v_mov_b32_e32 v58, 0
	v_mov_b32_e32 v59, 0
	v_mov_b32_e32 v60, 0
	v_mov_b32_e32 v61, 0
	v_mov_b32_e32 v62, 0
	v_mov_b32_e32 v63, 0
	v_mov_b32_e32 v64, 0
	v_mov_b32_e32 v65, 0
	v_cvt_pk_bf16_f32 v46, v46, v47
	v_cvt_pk_bf16_f32 v47, v48, v49
	v_cvt_pk_bf16_f32 v48, v42, v43
	v_cvt_pk_bf16_f32 v49, v44, v45
	v_lshl_add_u64 v[172:173], v[158:159], 1, v[172:173]
	v_cvt_pk_bf16_f32 v38, v38, v39
	v_cvt_pk_bf16_f32 v39, v40, v41
	v_cvt_pk_bf16_f32 v40, v34, v35
	v_cvt_pk_bf16_f32 v41, v36, v37
	global_store_dwordx4 v[172:173], v[46:49], off sc1 nt
	global_store_dwordx4 v[172:173], v[38:41], off offset:256 sc1 nt
	v_add_u32_e32 v174, 0xa0, v170
	v_mov_b64_e32 v[172:173], s[12:13]
	v_mad_i64_i32 v[172:173], s[0:1], v174, s43, v[172:173]
	v_mov_b32_e32 v34, 0
	v_mov_b32_e32 v35, 0
	v_mov_b32_e32 v36, 0
	v_mov_b32_e32 v37, 0
	v_mov_b32_e32 v38, 0
	v_mov_b32_e32 v39, 0
	v_mov_b32_e32 v40, 0
	v_mov_b32_e32 v41, 0
	v_mov_b32_e32 v42, 0
	v_mov_b32_e32 v43, 0
	v_mov_b32_e32 v44, 0
	v_mov_b32_e32 v45, 0
	v_mov_b32_e32 v46, 0
	v_mov_b32_e32 v47, 0
	v_mov_b32_e32 v48, 0
	v_mov_b32_e32 v49, 0
	v_cvt_pk_bf16_f32 v30, v30, v31
	v_cvt_pk_bf16_f32 v31, v32, v33
	v_cvt_pk_bf16_f32 v32, v26, v27
	v_cvt_pk_bf16_f32 v33, v28, v29
	v_lshl_add_u64 v[172:173], v[158:159], 1, v[172:173]
	v_cvt_pk_bf16_f32 v22, v22, v23
	v_cvt_pk_bf16_f32 v23, v24, v25
	v_cvt_pk_bf16_f32 v24, v18, v19
	v_cvt_pk_bf16_f32 v25, v20, v21
	global_store_dwordx4 v[172:173], v[30:33], off sc1 nt
	global_store_dwordx4 v[172:173], v[22:25], off offset:256 sc1 nt
	v_add_u32_e32 v174, 0xb0, v170
	v_mov_b64_e32 v[172:173], s[12:13]
	v_mad_i64_i32 v[172:173], s[0:1], v174, s43, v[172:173]
	v_mov_b32_e32 v18, 0
	v_mov_b32_e32 v19, 0
	v_mov_b32_e32 v20, 0
	v_mov_b32_e32 v21, 0
	v_mov_b32_e32 v22, 0
	v_mov_b32_e32 v23, 0
	v_mov_b32_e32 v24, 0
	v_mov_b32_e32 v25, 0
	v_mov_b32_e32 v26, 0
	v_mov_b32_e32 v27, 0
	v_mov_b32_e32 v28, 0
	v_mov_b32_e32 v29, 0
	v_mov_b32_e32 v30, 0
	v_mov_b32_e32 v31, 0
	v_mov_b32_e32 v32, 0
	v_mov_b32_e32 v33, 0
	v_cvt_pk_bf16_f32 v14, v14, v15
	v_cvt_pk_bf16_f32 v15, v16, v17
	v_cvt_pk_bf16_f32 v16, v10, v11
	v_cvt_pk_bf16_f32 v17, v12, v13
	v_lshl_add_u64 v[172:173], v[158:159], 1, v[172:173]
	v_cvt_pk_bf16_f32 v6, v6, v7
	v_cvt_pk_bf16_f32 v7, v8, v9
	v_cvt_pk_bf16_f32 v8, v2, v3
	v_cvt_pk_bf16_f32 v9, v4, v5
	global_store_dwordx4 v[172:173], v[14:17], off sc1 nt
	global_store_dwordx4 v[172:173], v[6:9], off offset:256 sc1 nt
	s_nop 1
	v_mov_b32_e32 v2, 0
	v_mov_b32_e32 v3, 0
	v_mov_b32_e32 v4, 0
	v_mov_b32_e32 v5, 0
	v_mov_b32_e32 v6, 0
	v_mov_b32_e32 v7, 0
	v_mov_b32_e32 v8, 0
	v_mov_b32_e32 v9, 0
	v_mov_b32_e32 v10, 0
	v_mov_b32_e32 v11, 0
	v_mov_b32_e32 v12, 0
	v_mov_b32_e32 v13, 0
	v_mov_b32_e32 v14, 0
	v_mov_b32_e32 v15, 0
	v_mov_b32_e32 v16, 0
	v_mov_b32_e32 v17, 0
	s_branch .Lepi_join
